# grid barriers after the phases whose stores are all write-through (P2, P3, P5): the XCD leader skips the L2 write-back (nothing dirty; sc1 payload + vmcnt(0) publish form)
# speedup vs baseline: 1.1888x; 1.0008x over previous
; __device__ __forceinline__ unsigned xb_ld(unsigned* p)              { return __hip_atomic_load(p, __ATOMIC_RELAXED, __HIP_MEMORY_SCOPE_AGENT); }
; __device__ __forceinline__ unsigned xb_add(unsigned* p, unsigned v) { return __hip_atomic_fetch_add(p, v, __ATOMIC_RELAXED, __HIP_MEMORY_SCOPE_AGENT); }
; #define XB_SPIN(cond, bar) do { unsigned _sp = 0; while (cond) { __builtin_amdgcn_s_sleep(1); \
;     if ((++_sp & 255u) == 0u) { if (xb_ld(&(bar)[XB_TMO])) break; if (_sp > XB_SPIN_CAP) { atomicAdd(&(bar)[XB_TMO], 1u); break; } } } } while (0)
; __device__ __forceinline__ void xcd_barrier(const XcdBarrier& b) {
;     ...
;         const unsigned old = xb_add(&bar[XB_XSUB(b.x)], 1u);
;         const unsigned gen = old / nloc;
;         if (old + 1u == (gen + 1u) * nloc) {
;             __builtin_amdgcn_fence(__ATOMIC_RELEASE, "agent");
;             asm volatile("s_waitcnt vmcnt(0)" ::: "memory");
;             const unsigned og = xb_add(&bar[XB_TOP], 1u);
;             const unsigned tg = og / nx;
;             if (og + 1u == (tg + 1u) * nx) xb_add(&bar[XB_TOPGEN], 1u);
;             else XB_SPIN(xb_ld(&bar[XB_TOPGEN]) == tg, bar);
;             __builtin_amdgcn_fence(__ATOMIC_ACQUIRE, "agent");
;             xb_add(&bar[XB_XGEN(b.x)], 1u);
;             asm volatile("s_waitcnt vmcnt(0)" ::: "memory");
.LBB0_365:
	s_andn2_saveexec_b64 s[8:9], s[8:9]
	s_cbranch_execz .LBB0_385
	s_mov_b64 s[8:9], exec
	s_nop 0
	s_waitcnt lgkmcnt(0)
	s_waitcnt vmcnt(0)
	v_mbcnt_lo_u32_b32 v1, s8, 0
	v_mbcnt_hi_u32_b32 v1, s9, v1
	v_cmp_eq_u32_e32 vcc, 0, v1
	s_and_saveexec_b64 s[10:11], vcc
	s_cbranch_execz .LBB0_368
	s_bcnt1_i32_b64 s8, s[8:9]
	v_mov_b32_e32 v2, 0x3000
	v_mov_b32_e32 v3, s8
	global_atomic_add v2, v2, v3, s[68:69] offset:1024 sc0

; __device__ __forceinline__ unsigned xb_ld(unsigned* p)              { return __hip_atomic_load(p, __ATOMIC_RELAXED, __HIP_MEMORY_SCOPE_AGENT); }
; __device__ __forceinline__ unsigned xb_add(unsigned* p, unsigned v) { return __hip_atomic_fetch_add(p, v, __ATOMIC_RELAXED, __HIP_MEMORY_SCOPE_AGENT); }
; #define XB_SPIN(cond, bar) do { unsigned _sp = 0; while (cond) { __builtin_amdgcn_s_sleep(1); \
;     if ((++_sp & 255u) == 0u) { if (xb_ld(&(bar)[XB_TMO])) break; if (_sp > XB_SPIN_CAP) { atomicAdd(&(bar)[XB_TMO], 1u); break; } } } } while (0)
; __device__ __forceinline__ void xcd_barrier(const XcdBarrier& b) {
;     ...
;         const unsigned old = xb_add(&bar[XB_XSUB(b.x)], 1u);
;         const unsigned gen = old / nloc;
;         if (old + 1u == (gen + 1u) * nloc) {
;             __builtin_amdgcn_fence(__ATOMIC_RELEASE, "agent");
;             asm volatile("s_waitcnt vmcnt(0)" ::: "memory");
;             const unsigned og = xb_add(&bar[XB_TOP], 1u);
;             const unsigned tg = og / nx;
;             if (og + 1u == (tg + 1u) * nx) xb_add(&bar[XB_TOPGEN], 1u);
;             else XB_SPIN(xb_ld(&bar[XB_TOPGEN]) == tg, bar);
;             __builtin_amdgcn_fence(__ATOMIC_ACQUIRE, "agent");
;             xb_add(&bar[XB_XGEN(b.x)], 1u);
;             asm volatile("s_waitcnt vmcnt(0)" ::: "memory");
.LBB0_458:
	s_andn2_saveexec_b64 s[10:11], s[10:11]
	s_cbranch_execz .LBB0_478
	s_mov_b64 s[10:11], exec
	s_nop 0
	s_waitcnt lgkmcnt(0)
	s_waitcnt vmcnt(0)
	v_mbcnt_lo_u32_b32 v1, s10, 0
	v_mbcnt_hi_u32_b32 v1, s11, v1
	v_cmp_eq_u32_e32 vcc, 0, v1
	s_and_saveexec_b64 s[12:13], vcc
	s_cbranch_execz .LBB0_461
	s_bcnt1_i32_b64 s10, s[10:11]
	v_mov_b32_e32 v2, 0x3000
	v_mov_b32_e32 v3, s10
	global_atomic_add v2, v2, v3, s[68:69] offset:1024 sc0

; __device__ __forceinline__ unsigned xb_ld(unsigned* p)              { return __hip_atomic_load(p, __ATOMIC_RELAXED, __HIP_MEMORY_SCOPE_AGENT); }
; __device__ __forceinline__ unsigned xb_add(unsigned* p, unsigned v) { return __hip_atomic_fetch_add(p, v, __ATOMIC_RELAXED, __HIP_MEMORY_SCOPE_AGENT); }
; #define XB_SPIN(cond, bar) do { unsigned _sp = 0; while (cond) { __builtin_amdgcn_s_sleep(1); \
;     if ((++_sp & 255u) == 0u) { if (xb_ld(&(bar)[XB_TMO])) break; if (_sp > XB_SPIN_CAP) { atomicAdd(&(bar)[XB_TMO], 1u); break; } } } } while (0)
; __device__ __forceinline__ void xcd_barrier(const XcdBarrier& b) {
;     ...
;         const unsigned old = xb_add(&bar[XB_XSUB(b.x)], 1u);
;         const unsigned gen = old / nloc;
;         if (old + 1u == (gen + 1u) * nloc) {
;             __builtin_amdgcn_fence(__ATOMIC_RELEASE, "agent");
;             asm volatile("s_waitcnt vmcnt(0)" ::: "memory");
;             const unsigned og = xb_add(&bar[XB_TOP], 1u);
;             const unsigned tg = og / nx;
;             if (og + 1u == (tg + 1u) * nx) xb_add(&bar[XB_TOPGEN], 1u);
;             else XB_SPIN(xb_ld(&bar[XB_TOPGEN]) == tg, bar);
;             __builtin_amdgcn_fence(__ATOMIC_ACQUIRE, "agent");
;             xb_add(&bar[XB_XGEN(b.x)], 1u);
;             asm volatile("s_waitcnt vmcnt(0)" ::: "memory");
.LBB0_663:
	s_andn2_saveexec_b64 s[8:9], s[8:9]
	s_cbranch_execz .LBB0_683
	s_mov_b64 s[8:9], exec
	s_nop 0
	s_waitcnt lgkmcnt(0)
	s_waitcnt vmcnt(0)
	v_mbcnt_lo_u32_b32 v1, s8, 0
	v_mbcnt_hi_u32_b32 v1, s9, v1
	v_cmp_eq_u32_e32 vcc, 0, v1
	s_and_saveexec_b64 s[10:11], vcc
	s_cbranch_execz .LBB0_666
	s_bcnt1_i32_b64 s2, s[8:9]
	v_mov_b32_e32 v2, 0x3000
	v_mov_b32_e32 v3, s2
	global_atomic_add v2, v2, v3, s[68:69] offset:1024 sc0
